# mix1 HGRN chunk loop: next chunk's global loads issued before the staging barrier instead of after it (loads stay in flight across the barrier)
# baseline (speedup 1.0000x reference)
.LBB0_817:
	s_or_b64 exec, exec, s[42:43]
	s_waitcnt vmcnt(0)
	v_sub_f32_e32 v147, v60, v40
	v_sub_f32_e32 v148, v60, v48
	v_mul_f32_e32 v147, 0x3fb8aa3b, v147
	v_mul_f32_e32 v148, 0x3fb8aa3b, v148
	v_exp_f32_e32 v147, v147
	v_exp_f32_e32 v148, v148
	v_sub_f32_e32 v145, v61, v41
	v_sub_f32_e32 v146, v61, v49
	v_mul_f32_e32 v145, 0x3fb8aa3b, v145
	v_mul_f32_e32 v146, 0x3fb8aa3b, v146
	v_lshlrev_b32_e32 v149, 16, v14
	v_lshlrev_b32_e32 v150, 16, v18
	v_exp_f32_e32 v145, v145
	v_exp_f32_e32 v146, v146
	v_mul_f32_e32 v147, v147, v149
	v_mul_f32_e32 v148, v148, v150
	v_cvt_pk_bf16_f32 v147, v147, v148
	v_and_b32_e32 v148, 0xffff, v22
	v_sub_f32_e32 v143, v62, v42
	v_sub_f32_e32 v144, v62, v50
	v_lshl_or_b32 v148, v26, 16, v148
	v_mul_f32_e32 v143, 0x3fb8aa3b, v143
	v_mul_f32_e32 v144, 0x3fb8aa3b, v144
	ds_write2st64_b32 v83, v147, v148 offset1:72
	v_and_b32_e32 v147, 0xffff0000, v14
	v_and_b32_e32 v148, 0xffff0000, v18
	v_exp_f32_e32 v143, v143
	v_exp_f32_e32 v144, v144
	v_mul_f32_e32 v145, v145, v147
	v_mul_f32_e32 v146, v146, v148
	v_cvt_pk_bf16_f32 v145, v145, v146
	v_lshrrev_b32_e32 v146, 16, v22
	v_sub_f32_e32 v141, v63, v43
	v_sub_f32_e32 v142, v63, v51
	v_and_or_b32 v146, v26, s90, v146
	v_add_u32_e32 v147, 0x90, v83
	v_mul_f32_e32 v141, 0x3fb8aa3b, v141
	v_mul_f32_e32 v142, 0x3fb8aa3b, v142
	ds_write2st64_b32 v147, v145, v146 offset1:72
	v_lshlrev_b32_e32 v145, 16, v15
	v_lshlrev_b32_e32 v146, 16, v19
	v_exp_f32_e32 v141, v141
	v_exp_f32_e32 v142, v142
	v_mul_f32_e32 v143, v143, v145
	v_mul_f32_e32 v144, v144, v146
	v_cvt_pk_bf16_f32 v143, v143, v144
	v_and_b32_e32 v144, 0xffff, v23
	v_sub_f32_e32 v139, v56, v36
	v_sub_f32_e32 v140, v56, v52
	v_lshl_or_b32 v144, v27, 16, v144
	v_add_u32_e32 v145, 32, v83
	v_mul_f32_e32 v139, 0x3fb8aa3b, v139
	v_mul_f32_e32 v140, 0x3fb8aa3b, v140
	ds_write2st64_b32 v145, v143, v144 offset0:1 offset1:73
	v_and_b32_e32 v143, 0xffff0000, v15
	v_and_b32_e32 v144, 0xffff0000, v19
	v_exp_f32_e32 v139, v139
	v_exp_f32_e32 v140, v140
	v_mul_f32_e32 v141, v141, v143
	v_mul_f32_e32 v142, v142, v144
	v_cvt_pk_bf16_f32 v141, v141, v142
	v_lshrrev_b32_e32 v142, 16, v23
	v_sub_f32_e32 v137, v57, v37
	v_sub_f32_e32 v138, v57, v53
	v_and_or_b32 v142, v27, s90, v142
	v_add_u32_e32 v143, 0xb0, v83
	v_mul_f32_e32 v137, 0x3fb8aa3b, v137
	v_mul_f32_e32 v138, 0x3fb8aa3b, v138
	ds_write2st64_b32 v143, v141, v142 offset0:1 offset1:73
	v_lshlrev_b32_e32 v141, 16, v16
	v_lshlrev_b32_e32 v142, 16, v20
	v_exp_f32_e32 v137, v137
	v_exp_f32_e32 v138, v138
	v_mul_f32_e32 v139, v139, v141
	v_mul_f32_e32 v140, v140, v142
	v_cvt_pk_bf16_f32 v139, v139, v140
	v_and_b32_e32 v140, 0xffff, v24
	v_sub_f32_e32 v135, v58, v38
	v_sub_f32_e32 v136, v58, v54
	v_lshl_or_b32 v140, v28, 16, v140
	v_add_u32_e32 v141, 64, v83
	v_mul_f32_e32 v135, 0x3fb8aa3b, v135
	v_mul_f32_e32 v136, 0x3fb8aa3b, v136
	ds_write2st64_b32 v141, v139, v140 offset0:2 offset1:74
	v_and_b32_e32 v139, 0xffff0000, v16
	v_and_b32_e32 v140, 0xffff0000, v20
	v_exp_f32_e32 v135, v135
	v_exp_f32_e32 v136, v136
	v_mul_f32_e32 v137, v137, v139
	v_mul_f32_e32 v138, v138, v140
	v_cvt_pk_bf16_f32 v137, v137, v138
	v_lshrrev_b32_e32 v138, 16, v24
	v_sub_f32_e32 v133, v59, v39
	v_sub_f32_e32 v134, v59, v55
	v_and_or_b32 v138, v28, s90, v138
	v_add_u32_e32 v139, 0xd0, v83
	v_mul_f32_e32 v133, 0x3fb8aa3b, v133
	v_mul_f32_e32 v134, 0x3fb8aa3b, v134
	ds_write2st64_b32 v139, v137, v138 offset0:2 offset1:74
	v_lshlrev_b32_e32 v137, 16, v17
	v_lshlrev_b32_e32 v138, 16, v21
	v_exp_f32_e32 v133, v133
	v_exp_f32_e32 v134, v134
	v_mul_f32_e32 v135, v135, v137
	v_mul_f32_e32 v136, v136, v138
	v_cvt_pk_bf16_f32 v135, v135, v136
	v_and_b32_e32 v136, 0xffff, v25
	v_lshl_or_b32 v136, v29, 16, v136
	v_add_u32_e32 v137, 0x60, v83
	ds_write2st64_b32 v137, v135, v136 offset0:3 offset1:75
	v_and_b32_e32 v135, 0xffff0000, v17
	v_and_b32_e32 v136, 0xffff0000, v21
	v_mul_f32_e32 v133, v133, v135
	v_mul_f32_e32 v134, v134, v136
	v_cvt_pk_bf16_f32 v133, v133, v134
	v_lshrrev_b32_e32 v134, 16, v25
	v_and_or_b32 v134, v29, s90, v134
	v_add_u32_e32 v135, 0xf0, v83
	s_add_i32 s9, s9, 1
	ds_write2st64_b32 v135, v133, v134 offset0:3 offset1:75
	s_cmp_ge_u32 s9, s7
	v_mov_b32_e32 v134, v121
	s_cbranch_scc1 .Lm1h_last
	v_add_u32_e32 v16, s18, v115
	v_subrev_u32_e32 v36, 63, v16
	v_subrev_u32_e32 v16, 62, v16
	v_ashrrev_i32_e32 v37, 31, v36
	v_ashrrev_i32_e32 v17, 31, v16
	v_lshlrev_b64 v[14:15], 14, v[36:37]
	v_lshlrev_b64 v[16:17], 14, v[16:17]
	v_lshl_add_u64 v[22:23], s[36:37], 0, v[14:15]
	s_lshl_b32 s4, s8, 1
	v_lshl_add_u64 v[24:25], s[36:37], 0, v[16:17]
	s_mov_b32 s13, s5
	v_lshl_add_u64 v[14:15], v[22:23], 0, s[4:5]
	v_lshl_add_u64 v[16:17], v[24:25], 0, s[4:5]
	v_lshl_add_u64 v[22:23], v[22:23], 0, s[12:13]
	v_lshl_add_u64 v[24:25], v[24:25], 0, s[12:13]
	v_lshlrev_b64 v[36:37], 12, v[36:37]
	v_lshl_add_u64 v[14:15], v[14:15], 0, v[34:35]
	v_lshl_add_u64 v[18:19], v[16:17], 0, v[34:35]
	v_lshl_add_u64 v[22:23], v[22:23], 0, v[34:35]
	v_lshl_add_u64 v[26:27], v[24:25], 0, v[34:35]
	v_lshl_add_u64 v[48:49], v[84:85], 0, v[36:37]
	s_ashr_i32 s19, s18, 31
	global_load_dwordx4 v[14:17], v[14:15], off offset:2048
	s_nop 0
	global_load_dwordx4 v[18:21], v[18:19], off offset:2048
	s_nop 0
	global_load_dwordx4 v[22:25], v[22:23], off
	s_nop 0
	global_load_dwordx4 v[26:29], v[26:27], off
	s_lshl_b64 s[42:43], s[18:19], 12
	global_load_dwordx4 v[36:39], v[48:49], off offset:16
	global_load_dwordx4 v[40:43], v[48:49], off
	v_lshl_add_u64 v[52:53], v[48:49], 0, s[92:93]
	v_add_co_u32_e32 v48, vcc, 0x1000, v48
	s_add_u32 s42, s16, s42
	s_nop 0
	v_addc_co_u32_e32 v49, vcc, 0, v49, vcc
	s_addc_u32 s43, s17, s43
	global_load_dwordx4 v[48:51], v[48:49], off
	s_nop 0
	global_load_dwordx4 v[52:55], v[52:53], off offset:16
	s_nop 0
	global_load_dwordx4 v[56:59], v82, s[42:43] offset:16
	global_load_dwordx4 v[60:63], v82, s[42:43]
	v_mov_b32_e32 v134, v121
	s_and_saveexec_b64 s[44:45], s[38:39]
	s_cbranch_execz .Lm1h_nl
	v_lshl_add_u64 v[134:135], v[76:77], 2, s[42:43]
	global_load_dword v134, v[134:135], off
.Lm1h_nl:
	s_waitcnt lgkmcnt(0)
	s_barrier
	s_branch .LBB0_799
